# P8 a_ready hook rewritten by hand: both halo rows per thread, all loads of a chunk in flight (2 passes instead of 6 dependent batches)
# speedup vs baseline: 1.0393x; 1.0393x over previous
.LBB0_986:
	s_ashr_i32 s0, s3, 3
	s_add_i32 s0, s5, s0
	s_ashr_i32 s1, s0, 31
	s_lshr_b32 s1, s1, 26
	s_add_i32 s1, s0, s1
	s_ashr_i32 s3, s1, 6
	s_andn2_b32 s1, s1, 63
	s_sub_i32 s0, s0, s1
	s_bfe_i32 s1, s0, 0x80000
	s_bfe_u32 s1, s1, 0x3000c
	s_add_i32 s1, s0, s1
	s_bfe_i32 s4, s1, 0x80000
	s_and_b32 s1, s1, 0xf8
	s_sub_i32 s0, s0, s1
	s_lshl_b32 s3, s3, 3
	s_sext_i32_i16 s4, s4
	s_sext_i32_i8 s0, s0
	s_lshr_b32 s37, s4, 3
	s_add_i32 s3, s3, s0
	s_cmp_gt_i32 s3, 0
	s_cselect_b64 vcc, -1, 0
	s_lshl_b32 s29, s3, 2
	s_or_b32 s38, s29, 2
	s_lshl_b32 s39, s3, 8
	s_add_u32 s12, s20, 0x5800
	s_addc_u32 s13, s21, 0
	s_waitcnt vmcnt(35)
	v_cndmask_b32_e64 v2, 0, 1.0, vcc
	s_add_u32 s16, s18, 0x5800
	v_lshlrev_b32_e32 v148, 3, v0
	s_waitcnt vmcnt(32)
	v_mov_b32_e32 v3, v2
	s_mov_b64 s[6:7], 0x5800
	s_addc_u32 s17, s19, 0
	s_mov_b64 s[10:11], 0
	s_movk_i32 s40, 0x2bf
	s_mov_b32 s41, 0xb000
	s_waitcnt vmcnt(30) lgkmcnt(1)
	v_mov_b64_e32 v[4:5], s[44:45]
	s_movk_i32 s42, 0x2c0
	s_waitcnt vmcnt(28) lgkmcnt(0)
	v_mov_b32_e32 v7, 0
	s_mov_b64 s[22:23], 0xb000
	s_mov_b64 s[30:31], 0x16000
	s_mov_b32 s43, 0x16000
	v_mov_b32_e32 v8, v2
	s_waitcnt vmcnt(26)
	v_mov_b32_e32 v9, v2
	s_movk_i32 s46, 0x5000
	s_movk_i32 s47, 0x2c00
	s_waitcnt vmcnt(24)
	v_mov_b64_e32 v[10:11], s[54:55]
	s_movk_i32 s48, 0x37f
	v_mov_b32_e32 v1, v148
	s_waitcnt vmcnt(21)
	v_mov_b32_e32 v16, v0
	v_readlane_b32 s60, v254, 2
	v_readlane_b32 s62, v254, 0
	v_readlane_b32 s63, v254, 1
	s_sub_u32 s62, s62, 0xc8
	s_subb_u32 s63, s63, 0
	s_load_dwordx4 s[64:67], s[62:63], 0x98
	s_and_b32 s61, s60, 7
	s_lshr_b32 s59, s60, 3
	s_lshl_b32 s61, s61, 5
	s_add_i32 s61, s61, s59
	s_lshr_b32 s59, s61, 6
	s_and_b32 s61, s61, 7
	s_lshl_b32 s59, s59, 3
	s_add_i32 s60, s59, s61
	s_cmp_lg_u32 s60, 0
	s_cselect_b32 s74, 1.0, 0
	s_mov_b32 s75, s74
	s_mov_b32 s68, 0x3d922279
	s_mov_b32 s70, 0x3fcc422a
	s_mov_b32 s72, 0xbfb8aa3b
	s_lshl_b32 s59, s60, 2
	s_add_u32 s82, s26, 0x18500000
	s_addc_u32 s83, s27, 0
	s_add_i32 s61, s59, 1
	s_max_i32 s61, s61, 0
	s_mul_i32 s61, s61, 0xb000
	s_add_u32 s88, s82, s61
	s_addc_u32 s89, s83, 0
	s_add_i32 s61, s59, 0
	s_max_i32 s61, s61, 0
	s_mul_i32 s61, s61, 0xb000
	s_add_u32 s86, s82, s61
	s_addc_u32 s87, s83, 0
	s_add_i32 s61, s59, -1
	s_max_i32 s61, s61, 0
	s_mul_i32 s61, s61, 0xb000
	s_add_u32 s84, s82, s61
	s_addc_u32 s85, s83, 0
	s_add_i32 s61, s59, -2
	s_max_i32 s61, s61, 0
	s_mul_i32 s61, s61, 0xb000
	s_add_u32 s82, s82, s61
	s_addc_u32 s83, s83, 0
	s_mul_i32 s61, s60, 0x2c0000
	s_add_u32 s90, s26, 0x7d00000
	s_addc_u32 s91, s27, 0
	s_add_u32 s90, s90, s61
	s_addc_u32 s91, s91, 0
	s_add_u32 s92, s90, 0x2c00
	s_addc_u32 s93, s91, 0
	s_waitcnt lgkmcnt(0)
	s_add_u32 s38, s64, 0x0
	s_addc_u32 s39, s65, 0
	s_add_u32 s40, s64, 0xb000
	s_addc_u32 s41, s65, 0
	s_add_u32 s42, s64, 0x16000
	s_addc_u32 s43, s65, 0
	v_lshlrev_b32_e32 v2, 5, v0
	v_add_u32_e32 v3, 0x5800, v2
	v_lshlrev_b32_e32 v4, 4, v0
	global_load_dwordx4 v[8:11], v2, s[66:67]
	global_load_dwordx4 v[12:15], v2, s[38:39]
	global_load_dwordx4 v[16:19], v2, s[40:41]
	global_load_dwordx4 v[20:23], v2, s[42:43]
	global_load_dwordx4 v[24:27], v2, s[82:83]
	global_load_dwordx4 v[28:31], v2, s[84:85]
	global_load_dwordx4 v[32:35], v2, s[86:87]
	global_load_dwordx4 v[36:39], v2, s[88:89]
	global_load_dwordx4 v[40:43], v2, s[66:67] offset:16
	global_load_dwordx4 v[44:47], v2, s[38:39] offset:16
	global_load_dwordx4 v[48:51], v2, s[40:41] offset:16
	global_load_dwordx4 v[52:55], v2, s[42:43] offset:16
	global_load_dwordx4 v[56:59], v2, s[82:83] offset:16
	global_load_dwordx4 v[60:63], v2, s[84:85] offset:16
	global_load_dwordx4 v[64:67], v2, s[86:87] offset:16
	global_load_dwordx4 v[68:71], v2, s[88:89] offset:16
	global_load_dwordx4 v[72:75], v3, s[66:67]
	global_load_dwordx4 v[76:79], v3, s[38:39]
	global_load_dwordx4 v[80:83], v3, s[40:41]
	global_load_dwordx4 v[84:87], v3, s[42:43]
	global_load_dwordx4 v[88:91], v3, s[82:83]
	global_load_dwordx4 v[92:95], v3, s[84:85]
	global_load_dwordx4 v[96:99], v3, s[86:87]
	global_load_dwordx4 v[100:103], v3, s[88:89]
	global_load_dwordx4 v[104:107], v3, s[66:67] offset:16
	global_load_dwordx4 v[108:111], v3, s[38:39] offset:16
	global_load_dwordx4 v[112:115], v3, s[40:41] offset:16
	global_load_dwordx4 v[116:119], v3, s[42:43] offset:16
	global_load_dwordx4 v[120:123], v3, s[82:83] offset:16
	global_load_dwordx4 v[124:127], v3, s[84:85] offset:16
	global_load_dwordx4 v[128:131], v3, s[86:87] offset:16
	global_load_dwordx4 v[132:135], v3, s[88:89] offset:16
	s_waitcnt vmcnt(0)
	v_pk_mul_f32 v[136:137], v[12:13], s[74:75] op_sel_hi:[1,0]
	v_pk_mul_f32 v[140:141], v[16:17], s[74:75] op_sel_hi:[1,0]
	v_pk_mul_f32 v[138:139], v[14:15], s[74:75] op_sel_hi:[1,0]
	v_pk_mul_f32 v[142:143], v[18:19], s[74:75] op_sel_hi:[1,0]
	v_pk_fma_f32 v[24:25], v[136:137], v[24:25], v[8:9]
	v_pk_fma_f32 v[8:9], v[136:137], v[28:29], v[8:9]
	v_pk_fma_f32 v[26:27], v[138:139], v[26:27], v[10:11]
	v_pk_fma_f32 v[10:11], v[138:139], v[30:31], v[10:11]
	v_pk_fma_f32 v[24:25], v[140:141], v[28:29], v[24:25]
	v_pk_fma_f32 v[8:9], v[16:17], v[32:33], v[8:9]
	v_pk_fma_f32 v[26:27], v[142:143], v[30:31], v[26:27]
	v_pk_fma_f32 v[10:11], v[18:19], v[34:35], v[10:11]
	v_pk_fma_f32 v[24:25], v[20:21], v[32:33], v[24:25]
	v_pk_fma_f32 v[8:9], v[20:21], v[36:37], v[8:9]
	v_pk_fma_f32 v[26:27], v[22:23], v[34:35], v[26:27]
	v_pk_fma_f32 v[10:11], v[22:23], v[38:39], v[10:11]
	v_pk_mul_f32 v[136:137], v[44:45], s[74:75] op_sel_hi:[1,0]
	v_pk_mul_f32 v[140:141], v[48:49], s[74:75] op_sel_hi:[1,0]
	v_pk_mul_f32 v[138:139], v[46:47], s[74:75] op_sel_hi:[1,0]
	v_pk_mul_f32 v[142:143], v[50:51], s[74:75] op_sel_hi:[1,0]
	v_pk_fma_f32 v[56:57], v[136:137], v[56:57], v[40:41]
	v_pk_fma_f32 v[40:41], v[136:137], v[60:61], v[40:41]
	v_pk_fma_f32 v[58:59], v[138:139], v[58:59], v[42:43]
	v_pk_fma_f32 v[42:43], v[138:139], v[62:63], v[42:43]
	v_pk_fma_f32 v[56:57], v[140:141], v[60:61], v[56:57]
	v_pk_fma_f32 v[40:41], v[48:49], v[64:65], v[40:41]
	v_pk_fma_f32 v[58:59], v[142:143], v[62:63], v[58:59]
	v_pk_fma_f32 v[42:43], v[50:51], v[66:67], v[42:43]
	v_pk_fma_f32 v[56:57], v[52:53], v[64:65], v[56:57]
	v_pk_fma_f32 v[40:41], v[52:53], v[68:69], v[40:41]
	v_pk_fma_f32 v[58:59], v[54:55], v[66:67], v[58:59]
	v_pk_fma_f32 v[42:43], v[54:55], v[70:71], v[42:43]
	v_pk_mul_f32 v[136:137], v[76:77], s[74:75] op_sel_hi:[1,0]
	v_pk_mul_f32 v[140:141], v[80:81], s[74:75] op_sel_hi:[1,0]
	v_pk_mul_f32 v[138:139], v[78:79], s[74:75] op_sel_hi:[1,0]
	v_pk_mul_f32 v[142:143], v[82:83], s[74:75] op_sel_hi:[1,0]
	v_pk_fma_f32 v[88:89], v[136:137], v[88:89], v[72:73]
	v_pk_fma_f32 v[72:73], v[136:137], v[92:93], v[72:73]
	v_pk_fma_f32 v[90:91], v[138:139], v[90:91], v[74:75]
	v_pk_fma_f32 v[74:75], v[138:139], v[94:95], v[74:75]
	v_pk_fma_f32 v[88:89], v[140:141], v[92:93], v[88:89]
	v_pk_fma_f32 v[72:73], v[80:81], v[96:97], v[72:73]
	v_pk_fma_f32 v[90:91], v[142:143], v[94:95], v[90:91]
	v_pk_fma_f32 v[74:75], v[82:83], v[98:99], v[74:75]
	v_pk_fma_f32 v[88:89], v[84:85], v[96:97], v[88:89]
	v_pk_fma_f32 v[72:73], v[84:85], v[100:101], v[72:73]
	v_pk_fma_f32 v[90:91], v[86:87], v[98:99], v[90:91]
	v_pk_fma_f32 v[74:75], v[86:87], v[102:103], v[74:75]
	v_pk_mul_f32 v[136:137], v[108:109], s[74:75] op_sel_hi:[1,0]
	v_pk_mul_f32 v[140:141], v[112:113], s[74:75] op_sel_hi:[1,0]
	v_pk_mul_f32 v[138:139], v[110:111], s[74:75] op_sel_hi:[1,0]
	v_pk_mul_f32 v[142:143], v[114:115], s[74:75] op_sel_hi:[1,0]
	v_pk_fma_f32 v[120:121], v[136:137], v[120:121], v[104:105]
	v_pk_fma_f32 v[104:105], v[136:137], v[124:125], v[104:105]
	v_pk_fma_f32 v[122:123], v[138:139], v[122:123], v[106:107]
	v_pk_fma_f32 v[106:107], v[138:139], v[126:127], v[106:107]
	v_pk_fma_f32 v[120:121], v[140:141], v[124:125], v[120:121]
	v_pk_fma_f32 v[104:105], v[112:113], v[128:129], v[104:105]
	v_pk_fma_f32 v[122:123], v[142:143], v[126:127], v[122:123]
	v_pk_fma_f32 v[106:107], v[114:115], v[130:131], v[106:107]
	v_pk_fma_f32 v[120:121], v[116:117], v[128:129], v[120:121]
	v_pk_fma_f32 v[104:105], v[116:117], v[132:133], v[104:105]
	v_pk_fma_f32 v[122:123], v[118:119], v[130:131], v[122:123]
	v_pk_fma_f32 v[106:107], v[118:119], v[134:135], v[106:107]
	v_pk_mul_f32 v[144:145], v[24:25], s[68:69] op_sel_hi:[1,0]
	v_pk_fma_f32 v[144:145], v[144:145], v[24:25], s[70:71] op_sel_hi:[1,1,0]
	v_pk_mul_f32 v[144:145], v[24:25], v[144:145]
	v_pk_mul_f32 v[144:145], v[144:145], s[72:73] op_sel_hi:[1,0]
	v_exp_f32_e32 v144, v144
	v_exp_f32_e32 v145, v145
	s_nop 0
	v_pk_add_f32 v[144:145], v[144:145], 1.0 op_sel_hi:[1,0]
	v_rcp_f32_e32 v144, v144
	v_rcp_f32_e32 v145, v145
	s_nop 0
	v_pk_mul_f32 v[144:145], v[24:25], v[144:145]
	v_pk_mul_f32 v[144:145], v[144:145], v[88:89]
	v_cvt_pk_bf16_f32 v150, v144, v145
	v_pk_mul_f32 v[144:145], v[26:27], s[68:69] op_sel_hi:[1,0]
	v_pk_fma_f32 v[144:145], v[144:145], v[26:27], s[70:71] op_sel_hi:[1,1,0]
	v_pk_mul_f32 v[144:145], v[26:27], v[144:145]
	v_pk_mul_f32 v[144:145], v[144:145], s[72:73] op_sel_hi:[1,0]
	v_exp_f32_e32 v144, v144
	v_exp_f32_e32 v145, v145
	s_nop 0
	v_pk_add_f32 v[144:145], v[144:145], 1.0 op_sel_hi:[1,0]
	v_rcp_f32_e32 v144, v144
	v_rcp_f32_e32 v145, v145
	s_nop 0
	v_pk_mul_f32 v[144:145], v[26:27], v[144:145]
	v_pk_mul_f32 v[144:145], v[144:145], v[90:91]
	v_cvt_pk_bf16_f32 v151, v144, v145
	v_pk_mul_f32 v[144:145], v[56:57], s[68:69] op_sel_hi:[1,0]
	v_pk_fma_f32 v[144:145], v[144:145], v[56:57], s[70:71] op_sel_hi:[1,1,0]
	v_pk_mul_f32 v[144:145], v[56:57], v[144:145]
	v_pk_mul_f32 v[144:145], v[144:145], s[72:73] op_sel_hi:[1,0]
	v_exp_f32_e32 v144, v144
	v_exp_f32_e32 v145, v145
	s_nop 0
	v_pk_add_f32 v[144:145], v[144:145], 1.0 op_sel_hi:[1,0]
	v_rcp_f32_e32 v144, v144
	v_rcp_f32_e32 v145, v145
	s_nop 0
	v_pk_mul_f32 v[144:145], v[56:57], v[144:145]
	v_pk_mul_f32 v[144:145], v[144:145], v[120:121]
	v_cvt_pk_bf16_f32 v152, v144, v145
	v_pk_mul_f32 v[144:145], v[58:59], s[68:69] op_sel_hi:[1,0]
	v_pk_fma_f32 v[144:145], v[144:145], v[58:59], s[70:71] op_sel_hi:[1,1,0]
	v_pk_mul_f32 v[144:145], v[58:59], v[144:145]
	v_pk_mul_f32 v[144:145], v[144:145], s[72:73] op_sel_hi:[1,0]
	v_exp_f32_e32 v144, v144
	v_exp_f32_e32 v145, v145
	s_nop 0
	v_pk_add_f32 v[144:145], v[144:145], 1.0 op_sel_hi:[1,0]
	v_rcp_f32_e32 v144, v144
	v_rcp_f32_e32 v145, v145
	s_nop 0
	v_pk_mul_f32 v[144:145], v[58:59], v[144:145]
	v_pk_mul_f32 v[144:145], v[144:145], v[122:123]
	v_cvt_pk_bf16_f32 v153, v144, v145
	global_store_dwordx4 v4, v[150:153], s[90:91]
	s_nop 1
	v_pk_mul_f32 v[144:145], v[8:9], s[68:69] op_sel_hi:[1,0]
	v_pk_fma_f32 v[144:145], v[144:145], v[8:9], s[70:71] op_sel_hi:[1,1,0]
	v_pk_mul_f32 v[144:145], v[8:9], v[144:145]
	v_pk_mul_f32 v[144:145], v[144:145], s[72:73] op_sel_hi:[1,0]
	v_exp_f32_e32 v144, v144
	v_exp_f32_e32 v145, v145
	s_nop 0
	v_pk_add_f32 v[144:145], v[144:145], 1.0 op_sel_hi:[1,0]
	v_rcp_f32_e32 v144, v144
	v_rcp_f32_e32 v145, v145
	s_nop 0
	v_pk_mul_f32 v[144:145], v[8:9], v[144:145]
	v_pk_mul_f32 v[144:145], v[144:145], v[72:73]
	v_cvt_pk_bf16_f32 v150, v144, v145
	v_pk_mul_f32 v[144:145], v[10:11], s[68:69] op_sel_hi:[1,0]
	v_pk_fma_f32 v[144:145], v[144:145], v[10:11], s[70:71] op_sel_hi:[1,1,0]
	v_pk_mul_f32 v[144:145], v[10:11], v[144:145]
	v_pk_mul_f32 v[144:145], v[144:145], s[72:73] op_sel_hi:[1,0]
	v_exp_f32_e32 v144, v144
	v_exp_f32_e32 v145, v145
	s_nop 0
	v_pk_add_f32 v[144:145], v[144:145], 1.0 op_sel_hi:[1,0]
	v_rcp_f32_e32 v144, v144
	v_rcp_f32_e32 v145, v145
	s_nop 0
	v_pk_mul_f32 v[144:145], v[10:11], v[144:145]
	v_pk_mul_f32 v[144:145], v[144:145], v[74:75]
	v_cvt_pk_bf16_f32 v151, v144, v145
	v_pk_mul_f32 v[144:145], v[40:41], s[68:69] op_sel_hi:[1,0]
	v_pk_fma_f32 v[144:145], v[144:145], v[40:41], s[70:71] op_sel_hi:[1,1,0]
	v_pk_mul_f32 v[144:145], v[40:41], v[144:145]
	v_pk_mul_f32 v[144:145], v[144:145], s[72:73] op_sel_hi:[1,0]
	v_exp_f32_e32 v144, v144
	v_exp_f32_e32 v145, v145
	s_nop 0
	v_pk_add_f32 v[144:145], v[144:145], 1.0 op_sel_hi:[1,0]
	v_rcp_f32_e32 v144, v144
	v_rcp_f32_e32 v145, v145
	s_nop 0
	v_pk_mul_f32 v[144:145], v[40:41], v[144:145]
	v_pk_mul_f32 v[144:145], v[144:145], v[104:105]
	v_cvt_pk_bf16_f32 v152, v144, v145
	v_pk_mul_f32 v[144:145], v[42:43], s[68:69] op_sel_hi:[1,0]
	v_pk_fma_f32 v[144:145], v[144:145], v[42:43], s[70:71] op_sel_hi:[1,1,0]
	v_pk_mul_f32 v[144:145], v[42:43], v[144:145]
	v_pk_mul_f32 v[144:145], v[144:145], s[72:73] op_sel_hi:[1,0]
	v_exp_f32_e32 v144, v144
	v_exp_f32_e32 v145, v145
	s_nop 0
	v_pk_add_f32 v[144:145], v[144:145], 1.0 op_sel_hi:[1,0]
	v_rcp_f32_e32 v144, v144
	v_rcp_f32_e32 v145, v145
	s_nop 0
	v_pk_mul_f32 v[144:145], v[42:43], v[144:145]
	v_pk_mul_f32 v[144:145], v[144:145], v[106:107]
	v_cvt_pk_bf16_f32 v153, v144, v145
	global_store_dwordx4 v4, v[150:153], s[92:93]
	s_nop 1
	v_readfirstlane_b32 s59, v0
	s_lshr_b32 s59, s59, 6
	s_cmp_gt_u32 s59, 2
	s_cbranch_scc1 .Lhook_done
	v_add_u32_e32 v2, 0x4000, v2
	v_add_u32_e32 v3, 0x4000, v3
	v_add_u32_e32 v4, 0x2000, v4
	global_load_dwordx4 v[8:11], v2, s[66:67]
	global_load_dwordx4 v[12:15], v2, s[38:39]
	global_load_dwordx4 v[16:19], v2, s[40:41]
	global_load_dwordx4 v[20:23], v2, s[42:43]
	global_load_dwordx4 v[24:27], v2, s[82:83]
	global_load_dwordx4 v[28:31], v2, s[84:85]
	global_load_dwordx4 v[32:35], v2, s[86:87]
	global_load_dwordx4 v[36:39], v2, s[88:89]
	global_load_dwordx4 v[40:43], v2, s[66:67] offset:16
	global_load_dwordx4 v[44:47], v2, s[38:39] offset:16
	global_load_dwordx4 v[48:51], v2, s[40:41] offset:16
	global_load_dwordx4 v[52:55], v2, s[42:43] offset:16
	global_load_dwordx4 v[56:59], v2, s[82:83] offset:16
	global_load_dwordx4 v[60:63], v2, s[84:85] offset:16
	global_load_dwordx4 v[64:67], v2, s[86:87] offset:16
	global_load_dwordx4 v[68:71], v2, s[88:89] offset:16
	global_load_dwordx4 v[72:75], v3, s[66:67]
	global_load_dwordx4 v[76:79], v3, s[38:39]
	global_load_dwordx4 v[80:83], v3, s[40:41]
	global_load_dwordx4 v[84:87], v3, s[42:43]
	global_load_dwordx4 v[88:91], v3, s[82:83]
	global_load_dwordx4 v[92:95], v3, s[84:85]
	global_load_dwordx4 v[96:99], v3, s[86:87]
	global_load_dwordx4 v[100:103], v3, s[88:89]
	global_load_dwordx4 v[104:107], v3, s[66:67] offset:16
	global_load_dwordx4 v[108:111], v3, s[38:39] offset:16
	global_load_dwordx4 v[112:115], v3, s[40:41] offset:16
	global_load_dwordx4 v[116:119], v3, s[42:43] offset:16
	global_load_dwordx4 v[120:123], v3, s[82:83] offset:16
	global_load_dwordx4 v[124:127], v3, s[84:85] offset:16
	global_load_dwordx4 v[128:131], v3, s[86:87] offset:16
	global_load_dwordx4 v[132:135], v3, s[88:89] offset:16
	s_waitcnt vmcnt(0)
	v_pk_mul_f32 v[136:137], v[12:13], s[74:75] op_sel_hi:[1,0]
	v_pk_mul_f32 v[140:141], v[16:17], s[74:75] op_sel_hi:[1,0]
	v_pk_mul_f32 v[138:139], v[14:15], s[74:75] op_sel_hi:[1,0]
	v_pk_mul_f32 v[142:143], v[18:19], s[74:75] op_sel_hi:[1,0]
	v_pk_fma_f32 v[24:25], v[136:137], v[24:25], v[8:9]
	v_pk_fma_f32 v[8:9], v[136:137], v[28:29], v[8:9]
	v_pk_fma_f32 v[26:27], v[138:139], v[26:27], v[10:11]
	v_pk_fma_f32 v[10:11], v[138:139], v[30:31], v[10:11]
	v_pk_fma_f32 v[24:25], v[140:141], v[28:29], v[24:25]
	v_pk_fma_f32 v[8:9], v[16:17], v[32:33], v[8:9]
	v_pk_fma_f32 v[26:27], v[142:143], v[30:31], v[26:27]
	v_pk_fma_f32 v[10:11], v[18:19], v[34:35], v[10:11]
	v_pk_fma_f32 v[24:25], v[20:21], v[32:33], v[24:25]
	v_pk_fma_f32 v[8:9], v[20:21], v[36:37], v[8:9]
	v_pk_fma_f32 v[26:27], v[22:23], v[34:35], v[26:27]
	v_pk_fma_f32 v[10:11], v[22:23], v[38:39], v[10:11]
	v_pk_mul_f32 v[136:137], v[44:45], s[74:75] op_sel_hi:[1,0]
	v_pk_mul_f32 v[140:141], v[48:49], s[74:75] op_sel_hi:[1,0]
	v_pk_mul_f32 v[138:139], v[46:47], s[74:75] op_sel_hi:[1,0]
	v_pk_mul_f32 v[142:143], v[50:51], s[74:75] op_sel_hi:[1,0]
	v_pk_fma_f32 v[56:57], v[136:137], v[56:57], v[40:41]
	v_pk_fma_f32 v[40:41], v[136:137], v[60:61], v[40:41]
	v_pk_fma_f32 v[58:59], v[138:139], v[58:59], v[42:43]
	v_pk_fma_f32 v[42:43], v[138:139], v[62:63], v[42:43]
	v_pk_fma_f32 v[56:57], v[140:141], v[60:61], v[56:57]
	v_pk_fma_f32 v[40:41], v[48:49], v[64:65], v[40:41]
	v_pk_fma_f32 v[58:59], v[142:143], v[62:63], v[58:59]
	v_pk_fma_f32 v[42:43], v[50:51], v[66:67], v[42:43]
	v_pk_fma_f32 v[56:57], v[52:53], v[64:65], v[56:57]
	v_pk_fma_f32 v[40:41], v[52:53], v[68:69], v[40:41]
	v_pk_fma_f32 v[58:59], v[54:55], v[66:67], v[58:59]
	v_pk_fma_f32 v[42:43], v[54:55], v[70:71], v[42:43]
	v_pk_mul_f32 v[136:137], v[76:77], s[74:75] op_sel_hi:[1,0]
	v_pk_mul_f32 v[140:141], v[80:81], s[74:75] op_sel_hi:[1,0]
	v_pk_mul_f32 v[138:139], v[78:79], s[74:75] op_sel_hi:[1,0]
	v_pk_mul_f32 v[142:143], v[82:83], s[74:75] op_sel_hi:[1,0]
	v_pk_fma_f32 v[88:89], v[136:137], v[88:89], v[72:73]
	v_pk_fma_f32 v[72:73], v[136:137], v[92:93], v[72:73]
	v_pk_fma_f32 v[90:91], v[138:139], v[90:91], v[74:75]
	v_pk_fma_f32 v[74:75], v[138:139], v[94:95], v[74:75]
	v_pk_fma_f32 v[88:89], v[140:141], v[92:93], v[88:89]
	v_pk_fma_f32 v[72:73], v[80:81], v[96:97], v[72:73]
	v_pk_fma_f32 v[90:91], v[142:143], v[94:95], v[90:91]
	v_pk_fma_f32 v[74:75], v[82:83], v[98:99], v[74:75]
	v_pk_fma_f32 v[88:89], v[84:85], v[96:97], v[88:89]
	v_pk_fma_f32 v[72:73], v[84:85], v[100:101], v[72:73]
	v_pk_fma_f32 v[90:91], v[86:87], v[98:99], v[90:91]
	v_pk_fma_f32 v[74:75], v[86:87], v[102:103], v[74:75]
	v_pk_mul_f32 v[136:137], v[108:109], s[74:75] op_sel_hi:[1,0]
	v_pk_mul_f32 v[140:141], v[112:113], s[74:75] op_sel_hi:[1,0]
	v_pk_mul_f32 v[138:139], v[110:111], s[74:75] op_sel_hi:[1,0]
	v_pk_mul_f32 v[142:143], v[114:115], s[74:75] op_sel_hi:[1,0]
	v_pk_fma_f32 v[120:121], v[136:137], v[120:121], v[104:105]
	v_pk_fma_f32 v[104:105], v[136:137], v[124:125], v[104:105]
	v_pk_fma_f32 v[122:123], v[138:139], v[122:123], v[106:107]
	v_pk_fma_f32 v[106:107], v[138:139], v[126:127], v[106:107]
	v_pk_fma_f32 v[120:121], v[140:141], v[124:125], v[120:121]
	v_pk_fma_f32 v[104:105], v[112:113], v[128:129], v[104:105]
	v_pk_fma_f32 v[122:123], v[142:143], v[126:127], v[122:123]
	v_pk_fma_f32 v[106:107], v[114:115], v[130:131], v[106:107]
	v_pk_fma_f32 v[120:121], v[116:117], v[128:129], v[120:121]
	v_pk_fma_f32 v[104:105], v[116:117], v[132:133], v[104:105]
	v_pk_fma_f32 v[122:123], v[118:119], v[130:131], v[122:123]
	v_pk_fma_f32 v[106:107], v[118:119], v[134:135], v[106:107]
	v_pk_mul_f32 v[144:145], v[24:25], s[68:69] op_sel_hi:[1,0]
	v_pk_fma_f32 v[144:145], v[144:145], v[24:25], s[70:71] op_sel_hi:[1,1,0]
	v_pk_mul_f32 v[144:145], v[24:25], v[144:145]
	v_pk_mul_f32 v[144:145], v[144:145], s[72:73] op_sel_hi:[1,0]
	v_exp_f32_e32 v144, v144
	v_exp_f32_e32 v145, v145
	s_nop 0
	v_pk_add_f32 v[144:145], v[144:145], 1.0 op_sel_hi:[1,0]
	v_rcp_f32_e32 v144, v144
	v_rcp_f32_e32 v145, v145
	s_nop 0
	v_pk_mul_f32 v[144:145], v[24:25], v[144:145]
	v_pk_mul_f32 v[144:145], v[144:145], v[88:89]
	v_cvt_pk_bf16_f32 v150, v144, v145
	v_pk_mul_f32 v[144:145], v[26:27], s[68:69] op_sel_hi:[1,0]
	v_pk_fma_f32 v[144:145], v[144:145], v[26:27], s[70:71] op_sel_hi:[1,1,0]
	v_pk_mul_f32 v[144:145], v[26:27], v[144:145]
	v_pk_mul_f32 v[144:145], v[144:145], s[72:73] op_sel_hi:[1,0]
	v_exp_f32_e32 v144, v144
	v_exp_f32_e32 v145, v145
	s_nop 0
	v_pk_add_f32 v[144:145], v[144:145], 1.0 op_sel_hi:[1,0]
	v_rcp_f32_e32 v144, v144
	v_rcp_f32_e32 v145, v145
	s_nop 0
	v_pk_mul_f32 v[144:145], v[26:27], v[144:145]
	v_pk_mul_f32 v[144:145], v[144:145], v[90:91]
	v_cvt_pk_bf16_f32 v151, v144, v145
	v_pk_mul_f32 v[144:145], v[56:57], s[68:69] op_sel_hi:[1,0]
	v_pk_fma_f32 v[144:145], v[144:145], v[56:57], s[70:71] op_sel_hi:[1,1,0]
	v_pk_mul_f32 v[144:145], v[56:57], v[144:145]
	v_pk_mul_f32 v[144:145], v[144:145], s[72:73] op_sel_hi:[1,0]
	v_exp_f32_e32 v144, v144
	v_exp_f32_e32 v145, v145
	s_nop 0
	v_pk_add_f32 v[144:145], v[144:145], 1.0 op_sel_hi:[1,0]
	v_rcp_f32_e32 v144, v144
	v_rcp_f32_e32 v145, v145
	s_nop 0
	v_pk_mul_f32 v[144:145], v[56:57], v[144:145]
	v_pk_mul_f32 v[144:145], v[144:145], v[120:121]
	v_cvt_pk_bf16_f32 v152, v144, v145
	v_pk_mul_f32 v[144:145], v[58:59], s[68:69] op_sel_hi:[1,0]
	v_pk_fma_f32 v[144:145], v[144:145], v[58:59], s[70:71] op_sel_hi:[1,1,0]
	v_pk_mul_f32 v[144:145], v[58:59], v[144:145]
	v_pk_mul_f32 v[144:145], v[144:145], s[72:73] op_sel_hi:[1,0]
	v_exp_f32_e32 v144, v144
	v_exp_f32_e32 v145, v145
	s_nop 0
	v_pk_add_f32 v[144:145], v[144:145], 1.0 op_sel_hi:[1,0]
	v_rcp_f32_e32 v144, v144
	v_rcp_f32_e32 v145, v145
	s_nop 0
	v_pk_mul_f32 v[144:145], v[58:59], v[144:145]
	v_pk_mul_f32 v[144:145], v[144:145], v[122:123]
	v_cvt_pk_bf16_f32 v153, v144, v145
	global_store_dwordx4 v4, v[150:153], s[90:91]
	s_nop 1
	v_pk_mul_f32 v[144:145], v[8:9], s[68:69] op_sel_hi:[1,0]
	v_pk_fma_f32 v[144:145], v[144:145], v[8:9], s[70:71] op_sel_hi:[1,1,0]
	v_pk_mul_f32 v[144:145], v[8:9], v[144:145]
	v_pk_mul_f32 v[144:145], v[144:145], s[72:73] op_sel_hi:[1,0]
	v_exp_f32_e32 v144, v144
	v_exp_f32_e32 v145, v145
	s_nop 0
	v_pk_add_f32 v[144:145], v[144:145], 1.0 op_sel_hi:[1,0]
	v_rcp_f32_e32 v144, v144
	v_rcp_f32_e32 v145, v145
	s_nop 0
	v_pk_mul_f32 v[144:145], v[8:9], v[144:145]
	v_pk_mul_f32 v[144:145], v[144:145], v[72:73]
	v_cvt_pk_bf16_f32 v150, v144, v145
	v_pk_mul_f32 v[144:145], v[10:11], s[68:69] op_sel_hi:[1,0]
	v_pk_fma_f32 v[144:145], v[144:145], v[10:11], s[70:71] op_sel_hi:[1,1,0]
	v_pk_mul_f32 v[144:145], v[10:11], v[144:145]
	v_pk_mul_f32 v[144:145], v[144:145], s[72:73] op_sel_hi:[1,0]
	v_exp_f32_e32 v144, v144
	v_exp_f32_e32 v145, v145
	s_nop 0
	v_pk_add_f32 v[144:145], v[144:145], 1.0 op_sel_hi:[1,0]
	v_rcp_f32_e32 v144, v144
	v_rcp_f32_e32 v145, v145
	s_nop 0
	v_pk_mul_f32 v[144:145], v[10:11], v[144:145]
	v_pk_mul_f32 v[144:145], v[144:145], v[74:75]
	v_cvt_pk_bf16_f32 v151, v144, v145
	v_pk_mul_f32 v[144:145], v[40:41], s[68:69] op_sel_hi:[1,0]
	v_pk_fma_f32 v[144:145], v[144:145], v[40:41], s[70:71] op_sel_hi:[1,1,0]
	v_pk_mul_f32 v[144:145], v[40:41], v[144:145]
	v_pk_mul_f32 v[144:145], v[144:145], s[72:73] op_sel_hi:[1,0]
	v_exp_f32_e32 v144, v144
	v_exp_f32_e32 v145, v145
	s_nop 0
	v_pk_add_f32 v[144:145], v[144:145], 1.0 op_sel_hi:[1,0]
	v_rcp_f32_e32 v144, v144
	v_rcp_f32_e32 v145, v145
	s_nop 0
	v_pk_mul_f32 v[144:145], v[40:41], v[144:145]
	v_pk_mul_f32 v[144:145], v[144:145], v[104:105]
	v_cvt_pk_bf16_f32 v152, v144, v145
	v_pk_mul_f32 v[144:145], v[42:43], s[68:69] op_sel_hi:[1,0]
	v_pk_fma_f32 v[144:145], v[144:145], v[42:43], s[70:71] op_sel_hi:[1,1,0]
	v_pk_mul_f32 v[144:145], v[42:43], v[144:145]
	v_pk_mul_f32 v[144:145], v[144:145], s[72:73] op_sel_hi:[1,0]
	v_exp_f32_e32 v144, v144
	v_exp_f32_e32 v145, v145
	s_nop 0
	v_pk_add_f32 v[144:145], v[144:145], 1.0 op_sel_hi:[1,0]
	v_rcp_f32_e32 v144, v144
	v_rcp_f32_e32 v145, v145
	s_nop 0
	v_pk_mul_f32 v[144:145], v[42:43], v[144:145]
	v_pk_mul_f32 v[144:145], v[144:145], v[106:107]
	v_cvt_pk_bf16_f32 v153, v144, v145
	global_store_dwordx4 v4, v[150:153], s[92:93]
	s_nop 1
.Lhook_done:
	v_lshlrev_b32_e32 v1, 4, v0
	v_and_b32_e32 v2, 32, v0
	v_lshrrev_b32_e32 v150, 1, v0
	v_lshrrev_b32_e32 v4, 5, v0
	v_bitop3_b32 v1, v1, v2, 48 bitop3:0x6c
	v_and_b32_e32 v2, 24, v150
	v_and_b32_e32 v4, 4, v4
	v_bfe_u32 v5, v0, 2, 2
	v_bfe_u32 v3, v0, 2, 4
	v_or3_b32 v2, v4, v5, v2
	v_lshrrev_b32_e32 v4, 3, v0
	v_and_or_b32 v1, v0, 64, v1
	v_and_or_b32 v5, v4, 48, v3
	v_and_or_b32 v4, v4, 32, v2
	v_lshrrev_b32_e32 v1, 1, v1
	v_mul_u32_u24_e32 v4, 0x1600, v4
	v_or_b32_e32 v4, v4, v1
	v_lshlrev_b32_e32 v152, 1, v4
	v_bfe_u32 v4, v0, 3, 25
	v_or_b32_e32 v4, 64, v4
	s_movk_i32 s0, 0x70
	s_lshr_b32 s11, s35, 6
	v_and_or_b32 v3, v4, s0, v3
	s_movk_i32 s0, 0x60
	v_and_or_b32 v2, v4, s0, v2
	s_lshl_b32 s0, s11, 10
	s_add_i32 s62, s0, 0
	s_mov_b32 s31, 0x20000
	v_mul_u32_u24_e32 v5, 0x1600, v5
	v_mul_u32_u24_e32 v3, 0x1600, v3
	v_mul_u32_u24_e32 v2, 0x1600, v2
	s_sext_i32_i8 s10, s37
	s_add_i32 s64, s62, 0x10000
	v_or_b32_e32 v5, v1, v5
	v_or_b32_e32 v3, v3, v1
	v_or_b32_e32 v1, v2, v1
	s_mov_b32 s38, 0x1600000
	s_and_b32 s37, s2, 0xffff
	s_mov_b32 s39, s31
	s_mul_i32 s63, s10, 0x2c0000
	s_waitcnt vmcnt(0)
	s_barrier
	s_mov_b32 m0, s64
	s_add_i32 s65, s62, 0x12000
	v_lshlrev_b32_e32 v154, 1, v1
	buffer_load_dwordx4 v152, s[36:39], s63 offen lds
	s_mov_b32 m0, s65
	s_add_i32 s66, s62, 0x14000
	buffer_load_dwordx4 v154, s[36:39], s63 offen lds
	s_add_i32 s0, s63, 0x160000
	s_mov_b32 m0, s66
	s_add_i32 s67, s62, 0x16000
	buffer_load_dwordx4 v152, s[36:39], s0 offen lds
	s_mov_b32 m0, s67
	s_mov_b32 s30, 0x5800000
	s_and_b32 s29, s55, 0xffff
	v_lshlrev_b32_e32 v151, 1, v5
	s_mul_i32 s61, s3, 0x2c0000
	buffer_load_dwordx4 v154, s[36:39], s0 offen lds
	s_mov_b32 m0, s62
	s_add_i32 s68, s62, 0x2000
	v_lshlrev_b32_e32 v153, 1, v3
	buffer_load_dwordx4 v151, s[28:31], s61 offen lds
	s_mov_b32 m0, s68
	s_add_i32 s69, s62, 0x4000
	buffer_load_dwordx4 v153, s[28:31], s61 offen lds
	s_add_i32 s0, s61, 0x160000
	s_mov_b32 m0, s69
	s_add_i32 s70, s62, 0x6000
	buffer_load_dwordx4 v151, s[28:31], s0 offen lds
	s_mov_b32 m0, s70
	s_lshr_b32 s59, s35, 8
	buffer_load_dwordx4 v153, s[28:31], s0 offen lds
	s_cmp_lg_u32 s59, 1
	s_mov_b32 s71, 0x16000
	s_cbranch_scc1 .LBB0_990
	s_barrier
